# out-projection EpiResid epilogues hand-written: gate once per tile, bf16 residual tile via LDS-DMA, LDS-transposed full-row stores
# speedup vs baseline: 1.0066x; 1.0009x over previous
.LBB0_101:
	s_cmp_gt_i32 s54, 5
	s_mov_b64 s[0:1], -1
	s_mov_b32 s2, s54
	s_cbranch_scc0 .LBB0_312
	v_readlane_b32 s0, v253, 55
	v_readlane_b32 s1, v253, 56
	s_andn2_b64 vcc, exec, s[0:1]
	s_cbranch_vccnz .LBB0_311
	v_readlane_b32 s0, v254, 55
	v_readlane_b32 s1, v254, 56
	s_and_b64 s[0:1], s[0:1], exec
	v_readlane_b32 s36, v252, 1
	v_readlane_b32 s39, v252, 4
	v_readlane_b32 s0, v254, 0
	v_readlane_b32 s4, v254, 53
	v_readlane_b32 s37, v252, 2
	v_readlane_b32 s38, v252, 3
	s_cselect_b32 s64, s39, s0
	v_readlane_b32 s0, v253, 63
	v_readlane_b32 s5, v254, 54
	s_cselect_b32 s96, s37, s25
	s_cselect_b32 s66, s36, s24
	s_cselect_b32 s62, s38, s0
	s_and_b64 s[0:1], s[4:5], exec
	s_cselect_b32 s0, 0x3c000, 0
	s_add_u32 s0, s86, s0
	s_addc_u32 s1, s87, 0
	s_add_u32 s6, s0, 0x4000
	v_readlane_b32 s40, v252, 5
	v_readlane_b32 s41, v252, 6
	v_readlane_b32 s42, v252, 7
	v_readlane_b32 s43, v252, 8
	v_readlane_b32 s44, v252, 9
	v_readlane_b32 s45, v252, 10
	v_readlane_b32 s46, v252, 11
	v_readlane_b32 s47, v252, 12
	v_readlane_b32 s48, v252, 13
	v_readlane_b32 s49, v252, 14
	v_readlane_b32 s50, v252, 15
	v_readlane_b32 s51, v252, 16
	s_addc_u32 s7, s1, 0
	s_and_b64 s[0:1], s[4:5], exec
	v_readlane_b32 s36, v253, 1
	s_cselect_b32 s0, 0x800000, 0
	v_readlane_b32 s44, v253, 9
	v_readlane_b32 s45, v253, 10
	s_add_u32 s57, s44, s0
	s_addc_u32 s63, s45, 0
	v_readlane_b32 s52, v254, 37
	v_readlane_b32 s53, v252, 0
	v_readlane_b32 s37, v253, 2
	v_readlane_b32 s38, v253, 3
	v_readlane_b32 s39, v253, 4
	v_readlane_b32 s40, v253, 5
	v_readlane_b32 s41, v253, 6
	v_readlane_b32 s42, v253, 7
	v_readlane_b32 s43, v253, 8
	v_readlane_b32 s46, v253, 11
	v_readlane_b32 s47, v253, 12
	v_readlane_b32 s48, v253, 13
	v_readlane_b32 s49, v253, 14
	v_readlane_b32 s50, v253, 15
	v_readlane_b32 s51, v253, 16
	s_branch .LBB0_105
.LBB0_105:
	s_ashr_i32 s0, s53, 1
	s_addk_i32 s0, 0x100
	s_ashr_i32 s1, s0, 31
	s_lshr_b32 s1, s1, 29
	s_add_i32 s1, s0, s1
	s_ashr_i32 s4, s1, 3
	s_and_b32 s1, s1, -8
	s_sub_i32 s0, s0, s1
	s_lshr_b32 s1, s0, 31
	s_or_b32 s1, s1, 48
	s_mul_i32 s56, s1, s0
	s_add_i32 s56, s56, s4
	s_mul_hi_i32 s0, s56, 0x2aaaaaab
	s_lshr_b32 s1, s0, 31
	s_ashr_i32 s76, s0, 5
	s_add_i32 s76, s76, s1
	s_lshl_b32 s4, s76, 2
	s_sub_i32 s0, 8, s4
	s_min_u32 s5, s0, 4
	s_mul_i32 s77, s76, 0xc0
	s_sub_i32 s8, s56, s77
	v_cvt_f32_ubyte0_e32 v2, s5
	v_cvt_f32_i32_e32 v0, s8
	v_rcp_iflag_f32_e32 v3, v2
	s_ashr_i32 s0, s8, 30
	s_waitcnt vmcnt(0)
	v_mov_b32_e32 v82, v206
	v_mul_f32_e32 v3, v0, v3
	v_trunc_f32_e32 v3, v3
	v_fma_f32 v0, -v3, v2, v0
	s_barrier
	s_or_b32 s9, s0, 1
	v_cmp_ge_f32_e64 s[0:1], |v0|, v2
	v_cvt_i32_f32_e32 v3, v3
	v_ashrrev_i32_e32 v0, 31, v82
	v_lshrrev_b32_e32 v0, 26, v0
	v_add_u32_e32 v0, v82, v0
	v_ashrrev_i32_e32 v4, 6, v0
	v_bfe_i32 v0, v82, 27, 1
	v_lshlrev_b32_e32 v87, 4, v82
	v_lshrrev_b32_e32 v0, 22, v0
	v_add_u32_e32 v0, v87, v0
	v_and_b32_e32 v0, 0xfffffc00, v0
	v_sub_u32_e32 v0, v87, v0
	v_lshrrev_b32_e32 v2, 4, v0
	v_bitop3_b32 v2, v2, v0, 32 bitop3:0x6c
	v_ashrrev_i32_e32 v0, 31, v0
	s_and_b64 s[0:1], s[0:1], exec
	v_lshrrev_b32_e32 v0, 26, v0
	v_readfirstlane_b32 s1, v3
	v_lshlrev_b32_e32 v3, 3, v4
	v_add_u32_e32 v0, v2, v0
	v_and_b32_e32 v3, 0xffff0, v3
	v_ashrrev_i32_e32 v5, 6, v0
	v_add_u32_e32 v0, v5, v3
	v_lshlrev_b32_e32 v3, 5, v4
	v_and_b32_e32 v6, 32, v3
	v_mul_i32_i24_e32 v3, 64, v5
	v_sub_u32_e32 v2, v2, v3
	v_ashrrev_i16_sdwa v2, v207, sext(v2) dst_sel:DWORD dst_unused:UNUSED_PAD src0_sel:DWORD src1_sel:BYTE_0
	v_add_u32_e32 v88, 0x2000, v87
	s_cselect_b32 s0, s9, 0
	v_bfe_i32 v8, v2, 0, 16
	v_ashrrev_i32_e32 v2, 31, v88
	s_add_i32 s54, s1, s0
	v_lshrrev_b32_e32 v2, 22, v2
	s_sext_i32_i16 s0, s54
	s_mul_i32 s54, s54, s5
	v_add_u32_e32 v2, v88, v2
	s_sub_i32 s1, s8, s54
	v_ashrrev_i32_e32 v7, 10, v2
	s_sext_i32_i16 s1, s1
	v_mul_i32_i24_e32 v2, 0x400, v7
	s_add_i32 s4, s4, s1
	s_lshl_b32 s1, s53, 7
	v_sub_u32_e32 v2, v88, v2
	s_lshl_b32 s8, s0, 8
	s_lshl_b32 s0, s4, 8
	s_and_b32 s1, s1, 0x80
	v_lshrrev_b32_e32 v3, 4, v2
	s_or_b32 s4, s0, s1
	v_bitop3_b32 v2, v3, v2, 32 bitop3:0x6c
	v_ashrrev_i32_e32 v9, 31, v2
	s_ashr_i32 s5, s4, 31
	v_lshrrev_b32_e32 v9, 26, v9
	s_lshl_b64 s[0:1], s[4:5], 12
	v_add_u32_e32 v11, v2, v9
	s_add_u32 s0, s57, s0
	v_lshlrev_b32_e32 v3, 3, v7
	v_ashrrev_i32_e32 v9, 6, v11
	v_and_b32_e32 v11, 0xc0, v11
	s_addc_u32 s1, s63, s1
	s_ashr_i32 s9, s8, 31
	v_readlane_b32 s36, v253, 33
	v_and_b32_e32 v3, 0xffff0, v3
	v_lshlrev_b32_e32 v10, 5, v7
	v_sub_u32_e32 v2, v2, v11
	v_add_u32_e32 v89, 0x10000, v87
	s_lshl_b64 s[10:11], s[8:9], 12
	v_readlane_b32 s48, v253, 45
	v_lshl_or_b32 v0, v0, 11, v6
	v_add_u32_e32 v3, v9, v3
	v_and_b32_e32 v10, 32, v10
	v_ashrrev_i16_sdwa v2, v207, sext(v2) dst_sel:DWORD dst_unused:UNUSED_PAD src0_sel:DWORD src1_sel:BYTE_0
	v_readfirstlane_b32 s5, v89
	v_add_u32_e32 v90, 0x12000, v87
	v_readlane_b32 s49, v253, 46
	s_add_u32 s12, s48, s10
	v_add_lshl_u32 v0, v0, v8, 1
	v_bfe_i32 v11, v2, 0, 16
	v_lshl_or_b32 v2, v3, 11, v10
	s_mov_b32 m0, s5
	v_readfirstlane_b32 s5, v90
	s_addc_u32 s13, s49, s11
	v_add_lshl_u32 v2, v2, v11, 1
	global_load_lds_dwordx4 v0, s[0:1]
	s_mov_b32 m0, s5
	v_readfirstlane_b32 s5, v87
	s_add_u32 s14, s0, 0x80000
	global_load_lds_dwordx4 v2, s[0:1]
	s_mov_b32 m0, s5
	v_readfirstlane_b32 s5, v88
	s_addc_u32 s15, s1, 0
	v_add_u32_e32 v91, 0x14000, v87
	s_or_b32 s16, s8, 0x80
	global_load_lds_dwordx4 v0, s[12:13]
	s_mov_b32 m0, s5
	v_readfirstlane_b32 s5, v91
	v_add_u32_e32 v92, 0x16000, v87
	s_ashr_i32 s17, s16, 31
	global_load_lds_dwordx4 v2, s[12:13]
	s_mov_b32 m0, s5
	v_readfirstlane_b32 s5, v92
	s_lshl_b64 s[16:17], s[16:17], 12
	v_add_u32_e32 v93, 0x4000, v87
	global_load_lds_dwordx4 v0, s[14:15]
	s_mov_b32 m0, s5
	s_add_u32 s16, s48, s16
	v_readfirstlane_b32 s5, v93
	v_add_u32_e32 v94, 0x6000, v87
	global_load_lds_dwordx4 v2, s[14:15]
	s_addc_u32 s17, s49, s17
	s_mov_b32 m0, s5
	v_readfirstlane_b32 s5, v94
	global_load_lds_dwordx4 v0, s[16:17]
	s_mov_b32 m0, s5
	v_ashrrev_i32_e32 v83, 8, v82
	global_load_lds_dwordx4 v2, s[16:17]
	v_cmp_eq_u32_e32 vcc, 1, v83
	v_readlane_b32 s37, v253, 34
	v_readlane_b32 s38, v253, 35
	v_readlane_b32 s39, v253, 36
	v_readlane_b32 s40, v253, 37
	v_readlane_b32 s41, v253, 38
	v_readlane_b32 s42, v253, 39
	v_readlane_b32 s43, v253, 40
	v_readlane_b32 s44, v253, 41
	v_readlane_b32 s45, v253, 42
	v_readlane_b32 s46, v253, 43
	v_readlane_b32 s47, v253, 44
	v_readlane_b32 s50, v253, 47
	v_readlane_b32 s51, v253, 48
	s_and_saveexec_b64 s[72:73], vcc
	s_cbranch_execz .LBB0_107
	s_barrier

.LBB0_111:
	s_or_b64 exec, exec, s[0:1]
	v_and_b32_e32 v130, 63, v206
	v_lshrrev_b32_e32 v131, 6, v206
	v_and_b32_e32 v132, 15, v206
	v_bfe_u32 v133, v206, 4, 2
	v_and_b32_e32 v134, 3, v131
	v_lshrrev_b32_e32 v135, 2, v131
	v_readfirstlane_b32 s0, v131
	s_sub_u32 s1, s8, 0x1000
	s_lshr_b32 s9, s1, 11
	s_add_u32 s9, s9, 1
	s_cmp_lt_u32 s8, 0x1000
	s_cselect_b32 s9, 0, s9
	s_cselect_b32 s1, s8, s1
	s_cselect_b32 s12, s66, s62
	s_cselect_b32 s13, s96, s64
	s_mul_i32 s9, s9, s65
	s_lshl_b32 s11, s4, 2
	s_add_u32 s14, s6, s9
	s_addc_u32 s15, s7, 0
	s_add_u32 s14, s14, s11
	s_addc_u32 s15, s15, 0
	s_lshl_b32 s9, s8, 12
	s_lshl_b32 s11, s4, 1
	s_add_u32 s16, s22, s9
	s_addc_u32 s17, s23, 0
	s_add_u32 s16, s16, s11
	s_addc_u32 s17, s17, 0
	v_lshlrev_b32_e32 v136, 5, v134
	v_lshl_add_u32 v136, v133, 2, v136
	v_lshlrev_b32_e32 v137, 2, v136
	global_load_dwordx4 v[142:145], v137, s[14:15]
	global_load_dwordx4 v[146:149], v137, s[14:15] offset:64
	s_cmp_lg_u64 s[70:71], 0
	s_cbranch_scc0 .Lres_oh_f32
	s_lshl_b32 s9, s1, 12
	s_add_u32 s12, s12, s9
	s_addc_u32 s13, s13, 0
	s_add_u32 s12, s12, s11
	s_addc_u32 s13, s13, 0
	v_lshrrev_b32_e32 v138, 4, v130
	v_lshl_add_u32 v139, v131, 2, v138
	v_and_b32_e32 v140, 15, v130
	v_and_b32_e32 v141, 15, v139
	v_xor_b32_e32 v140, v140, v141
	v_lshlrev_b32_e32 v141, 12, v139
	v_lshl_add_u32 v141, v140, 4, v141
	s_lshl_b32 s9, s0, 10
	s_mov_b32 m0, s9
	s_add_i32 s9, s9, 0x2000
	global_load_lds_dwordx4 v141, s[12:13]
	s_add_u32 s12, s12, 0x20000
	s_addc_u32 s13, s13, 0
	s_mov_b32 m0, s9
	s_add_i32 s9, s9, 0x2000
	global_load_lds_dwordx4 v141, s[12:13]
	s_add_u32 s12, s12, 0x20000
	s_addc_u32 s13, s13, 0
	s_mov_b32 m0, s9
	s_add_i32 s9, s9, 0x2000
	global_load_lds_dwordx4 v141, s[12:13]
	s_add_u32 s12, s12, 0x20000
	s_addc_u32 s13, s13, 0
	s_mov_b32 m0, s9
	s_add_i32 s9, s9, 0x2000
	global_load_lds_dwordx4 v141, s[12:13]
	s_add_u32 s12, s12, 0x20000
	s_addc_u32 s13, s13, 0
	s_mov_b32 m0, s9
	s_add_i32 s9, s9, 0x2000
	global_load_lds_dwordx4 v141, s[12:13]
	s_add_u32 s12, s12, 0x20000
	s_addc_u32 s13, s13, 0
	s_mov_b32 m0, s9
	s_add_i32 s9, s9, 0x2000
	global_load_lds_dwordx4 v141, s[12:13]
	s_add_u32 s12, s12, 0x20000
	s_addc_u32 s13, s13, 0
	s_mov_b32 m0, s9
	s_add_i32 s9, s9, 0x2000
	global_load_lds_dwordx4 v141, s[12:13]
	s_add_u32 s12, s12, 0x20000
	s_addc_u32 s13, s13, 0
	s_mov_b32 m0, s9
	s_add_i32 s9, s9, 0x2000
	global_load_lds_dwordx4 v141, s[12:13]
	v_lshrrev_b32_e32 v138, 1, v133
	v_lshl_add_u32 v138, v134, 2, v138
	v_and_b32_e32 v139, 1, v133
	v_lshlrev_b32_e32 v139, 3, v139
	v_lshl_add_u32 v140, v135, 6, v132
	v_lshlrev_b32_e32 v140, 8, v140
	v_add_u32_e32 v140, v140, v139
	v_mov_b32_e32 v141, v138
	v_xor_b32_e32 v141, v141, v132
	v_lshl_add_u32 v158, v141, 4, v140
	v_add_u32_e32 v141, 2, v138
	v_xor_b32_e32 v141, v141, v132
	v_lshl_add_u32 v159, v141, 4, v140
	s_waitcnt vmcnt(0)
	s_barrier
	ds_read_b64 v[162:163], v158
	ds_read_b64 v[164:165], v159
	s_waitcnt lgkmcnt(1)
	v_lshlrev_b32_e32 v166, 16, v162
	v_and_b32_e32 v167, 0xffff0000, v162
	v_lshlrev_b32_e32 v168, 16, v163
	v_and_b32_e32 v169, 0xffff0000, v163
	v_fma_f32 v62, v62, v142, v166
	v_fma_f32 v63, v63, v143, v167
	v_fma_f32 v64, v64, v144, v168
	v_fma_f32 v65, v65, v145, v169
	v_cvt_pk_bf16_f32 v62, v62, v63
	v_cvt_pk_bf16_f32 v63, v64, v65
	ds_read_b64 v[162:163], v158 offset:4096
	s_waitcnt lgkmcnt(1)
	v_lshlrev_b32_e32 v166, 16, v164
	v_and_b32_e32 v167, 0xffff0000, v164
	v_lshlrev_b32_e32 v168, 16, v165
	v_and_b32_e32 v169, 0xffff0000, v165
	v_fma_f32 v58, v58, v146, v166
	v_fma_f32 v59, v59, v147, v167
	v_fma_f32 v60, v60, v148, v168
	v_fma_f32 v61, v61, v149, v169
	v_cvt_pk_bf16_f32 v58, v58, v59
	v_cvt_pk_bf16_f32 v59, v60, v61
	ds_read_b64 v[164:165], v159 offset:4096
	s_waitcnt lgkmcnt(1)
	v_lshlrev_b32_e32 v166, 16, v162
	v_and_b32_e32 v167, 0xffff0000, v162
	v_lshlrev_b32_e32 v168, 16, v163
	v_and_b32_e32 v169, 0xffff0000, v163
	v_fma_f32 v54, v54, v142, v166
	v_fma_f32 v55, v55, v143, v167
	v_fma_f32 v56, v56, v144, v168
	v_fma_f32 v57, v57, v145, v169
	v_cvt_pk_bf16_f32 v54, v54, v55
	v_cvt_pk_bf16_f32 v55, v56, v57
	ds_read_b64 v[162:163], v158 offset:8192
	s_waitcnt lgkmcnt(1)
	v_lshlrev_b32_e32 v166, 16, v164
	v_and_b32_e32 v167, 0xffff0000, v164
	v_lshlrev_b32_e32 v168, 16, v165
	v_and_b32_e32 v169, 0xffff0000, v165
	v_fma_f32 v50, v50, v146, v166
	v_fma_f32 v51, v51, v147, v167
	v_fma_f32 v52, v52, v148, v168
	v_fma_f32 v53, v53, v149, v169
	v_cvt_pk_bf16_f32 v50, v50, v51
	v_cvt_pk_bf16_f32 v51, v52, v53
	ds_read_b64 v[164:165], v159 offset:8192
	s_waitcnt lgkmcnt(1)
	v_lshlrev_b32_e32 v166, 16, v162
	v_and_b32_e32 v167, 0xffff0000, v162
	v_lshlrev_b32_e32 v168, 16, v163
	v_and_b32_e32 v169, 0xffff0000, v163
	v_fma_f32 v46, v46, v142, v166
	v_fma_f32 v47, v47, v143, v167
	v_fma_f32 v48, v48, v144, v168
	v_fma_f32 v49, v49, v145, v169
	v_cvt_pk_bf16_f32 v46, v46, v47
	v_cvt_pk_bf16_f32 v47, v48, v49
	ds_read_b64 v[162:163], v158 offset:12288
	s_waitcnt lgkmcnt(1)
	v_lshlrev_b32_e32 v166, 16, v164
	v_and_b32_e32 v167, 0xffff0000, v164
	v_lshlrev_b32_e32 v168, 16, v165
	v_and_b32_e32 v169, 0xffff0000, v165
	v_fma_f32 v42, v42, v146, v166
	v_fma_f32 v43, v43, v147, v167
	v_fma_f32 v44, v44, v148, v168
	v_fma_f32 v45, v45, v149, v169
	v_cvt_pk_bf16_f32 v42, v42, v43
	v_cvt_pk_bf16_f32 v43, v44, v45
	ds_read_b64 v[164:165], v159 offset:12288
	s_waitcnt lgkmcnt(1)
	v_lshlrev_b32_e32 v166, 16, v162
	v_and_b32_e32 v167, 0xffff0000, v162
	v_lshlrev_b32_e32 v168, 16, v163
	v_and_b32_e32 v169, 0xffff0000, v163
	v_fma_f32 v38, v38, v142, v166
	v_fma_f32 v39, v39, v143, v167
	v_fma_f32 v40, v40, v144, v168
	v_fma_f32 v41, v41, v145, v169
	v_cvt_pk_bf16_f32 v38, v38, v39
	v_cvt_pk_bf16_f32 v39, v40, v41
	ds_read_b64 v[162:163], v158 offset:32768
	s_waitcnt lgkmcnt(1)
	v_lshlrev_b32_e32 v166, 16, v164
	v_and_b32_e32 v167, 0xffff0000, v164
	v_lshlrev_b32_e32 v168, 16, v165
	v_and_b32_e32 v169, 0xffff0000, v165
	v_fma_f32 v34, v34, v146, v166
	v_fma_f32 v35, v35, v147, v167
	v_fma_f32 v36, v36, v148, v168
	v_fma_f32 v37, v37, v149, v169
	v_cvt_pk_bf16_f32 v34, v34, v35
	v_cvt_pk_bf16_f32 v35, v36, v37
	ds_read_b64 v[164:165], v159 offset:32768
	s_waitcnt lgkmcnt(1)
	v_lshlrev_b32_e32 v166, 16, v162
	v_and_b32_e32 v167, 0xffff0000, v162
	v_lshlrev_b32_e32 v168, 16, v163
	v_and_b32_e32 v169, 0xffff0000, v163
	v_fma_f32 v30, v30, v142, v166
	v_fma_f32 v31, v31, v143, v167
	v_fma_f32 v32, v32, v144, v168
	v_fma_f32 v33, v33, v145, v169
	v_cvt_pk_bf16_f32 v30, v30, v31
	v_cvt_pk_bf16_f32 v31, v32, v33
	ds_read_b64 v[162:163], v158 offset:36864
	s_waitcnt lgkmcnt(1)
	v_lshlrev_b32_e32 v166, 16, v164
	v_and_b32_e32 v167, 0xffff0000, v164
	v_lshlrev_b32_e32 v168, 16, v165
	v_and_b32_e32 v169, 0xffff0000, v165
	v_fma_f32 v26, v26, v146, v166
	v_fma_f32 v27, v27, v147, v167
	v_fma_f32 v28, v28, v148, v168
	v_fma_f32 v29, v29, v149, v169
	v_cvt_pk_bf16_f32 v26, v26, v27
	v_cvt_pk_bf16_f32 v27, v28, v29
	ds_read_b64 v[164:165], v159 offset:36864
	s_waitcnt lgkmcnt(1)
	v_lshlrev_b32_e32 v166, 16, v162
	v_and_b32_e32 v167, 0xffff0000, v162
	v_lshlrev_b32_e32 v168, 16, v163
	v_and_b32_e32 v169, 0xffff0000, v163
	v_fma_f32 v22, v22, v142, v166
	v_fma_f32 v23, v23, v143, v167
	v_fma_f32 v24, v24, v144, v168
	v_fma_f32 v25, v25, v145, v169
	v_cvt_pk_bf16_f32 v22, v22, v23
	v_cvt_pk_bf16_f32 v23, v24, v25
	ds_read_b64 v[162:163], v158 offset:40960
	s_waitcnt lgkmcnt(1)
	v_lshlrev_b32_e32 v166, 16, v164
	v_and_b32_e32 v167, 0xffff0000, v164
	v_lshlrev_b32_e32 v168, 16, v165
	v_and_b32_e32 v169, 0xffff0000, v165
	v_fma_f32 v18, v18, v146, v166
	v_fma_f32 v19, v19, v147, v167
	v_fma_f32 v20, v20, v148, v168
	v_fma_f32 v21, v21, v149, v169
	v_cvt_pk_bf16_f32 v18, v18, v19
	v_cvt_pk_bf16_f32 v19, v20, v21
	ds_read_b64 v[164:165], v159 offset:40960
	s_waitcnt lgkmcnt(1)
	v_lshlrev_b32_e32 v166, 16, v162
	v_and_b32_e32 v167, 0xffff0000, v162
	v_lshlrev_b32_e32 v168, 16, v163
	v_and_b32_e32 v169, 0xffff0000, v163
	v_fma_f32 v14, v14, v142, v166
	v_fma_f32 v15, v15, v143, v167
	v_fma_f32 v16, v16, v144, v168
	v_fma_f32 v17, v17, v145, v169
	v_cvt_pk_bf16_f32 v14, v14, v15
	v_cvt_pk_bf16_f32 v15, v16, v17
	ds_read_b64 v[162:163], v158 offset:45056
	s_waitcnt lgkmcnt(1)
	v_lshlrev_b32_e32 v166, 16, v164
	v_and_b32_e32 v167, 0xffff0000, v164
	v_lshlrev_b32_e32 v168, 16, v165
	v_and_b32_e32 v169, 0xffff0000, v165
	v_fma_f32 v10, v10, v146, v166
	v_fma_f32 v11, v11, v147, v167
	v_fma_f32 v12, v12, v148, v168
	v_fma_f32 v13, v13, v149, v169
	v_cvt_pk_bf16_f32 v10, v10, v11
	v_cvt_pk_bf16_f32 v11, v12, v13
	ds_read_b64 v[164:165], v159 offset:45056
	s_waitcnt lgkmcnt(1)
	v_lshlrev_b32_e32 v166, 16, v162
	v_and_b32_e32 v167, 0xffff0000, v162
	v_lshlrev_b32_e32 v168, 16, v163
	v_and_b32_e32 v169, 0xffff0000, v163
	v_fma_f32 v6, v6, v142, v166
	v_fma_f32 v7, v7, v143, v167
	v_fma_f32 v8, v8, v144, v168
	v_fma_f32 v9, v9, v145, v169
	v_cvt_pk_bf16_f32 v6, v6, v7
	v_cvt_pk_bf16_f32 v7, v8, v9
	s_waitcnt lgkmcnt(0)
	v_lshlrev_b32_e32 v166, 16, v164
	v_and_b32_e32 v167, 0xffff0000, v164
	v_lshlrev_b32_e32 v168, 16, v165
	v_and_b32_e32 v169, 0xffff0000, v165
	v_fma_f32 v2, v2, v146, v166
	v_fma_f32 v3, v3, v147, v167
	v_fma_f32 v4, v4, v148, v168
	v_fma_f32 v5, v5, v149, v169
	v_cvt_pk_bf16_f32 v2, v2, v3
	v_cvt_pk_bf16_f32 v3, v4, v5
	s_branch .Lres_oh_store
.Lres_oh_f32:
	s_lshl_b32 s9, s1, 13
	s_add_u32 s12, s12, s9
	s_addc_u32 s13, s13, 0
	s_lshl_b32 s11, s4, 2
	s_add_u32 s12, s12, s11
	s_addc_u32 s13, s13, 0
	v_lshl_add_u32 v138, v135, 6, v132
	v_lshlrev_b32_e32 v138, 13, v138
	v_add_u32_e32 v138, v138, v137
	global_load_dwordx4 v[166:169], v138, s[12:13]
	global_load_dwordx4 v[170:173], v138, s[12:13] offset:64
	s_add_u32 s12, s12, 0x20000
	s_addc_u32 s13, s13, 0
	global_load_dwordx4 v[174:177], v138, s[12:13]
	global_load_dwordx4 v[178:181], v138, s[12:13] offset:64
	s_add_u32 s12, s12, 0x20000
	s_addc_u32 s13, s13, 0
	global_load_dwordx4 v[182:185], v138, s[12:13]
	global_load_dwordx4 v[186:189], v138, s[12:13] offset:64
	s_add_u32 s12, s12, 0x20000
	s_addc_u32 s13, s13, 0
	global_load_dwordx4 v[190:193], v138, s[12:13]
	global_load_dwordx4 v[194:197], v138, s[12:13] offset:64
	s_add_u32 s12, s12, 0xa0000
	s_addc_u32 s13, s13, 0
	s_waitcnt vmcnt(7)
	v_fma_f32 v62, v62, v142, v166
	v_fma_f32 v63, v63, v143, v167
	v_fma_f32 v64, v64, v144, v168
	v_fma_f32 v65, v65, v145, v169
	v_cvt_pk_bf16_f32 v62, v62, v63
	v_cvt_pk_bf16_f32 v63, v64, v65
	s_waitcnt vmcnt(6)
	v_fma_f32 v58, v58, v146, v170
	v_fma_f32 v59, v59, v147, v171
	v_fma_f32 v60, v60, v148, v172
	v_fma_f32 v61, v61, v149, v173
	v_cvt_pk_bf16_f32 v58, v58, v59
	v_cvt_pk_bf16_f32 v59, v60, v61
	s_waitcnt vmcnt(5)
	v_fma_f32 v54, v54, v142, v174
	v_fma_f32 v55, v55, v143, v175
	v_fma_f32 v56, v56, v144, v176
	v_fma_f32 v57, v57, v145, v177
	v_cvt_pk_bf16_f32 v54, v54, v55
	v_cvt_pk_bf16_f32 v55, v56, v57
	s_waitcnt vmcnt(4)
	v_fma_f32 v50, v50, v146, v178
	v_fma_f32 v51, v51, v147, v179
	v_fma_f32 v52, v52, v148, v180
	v_fma_f32 v53, v53, v149, v181
	v_cvt_pk_bf16_f32 v50, v50, v51
	v_cvt_pk_bf16_f32 v51, v52, v53
	s_waitcnt vmcnt(3)
	v_fma_f32 v46, v46, v142, v182
	v_fma_f32 v47, v47, v143, v183
	v_fma_f32 v48, v48, v144, v184
	v_fma_f32 v49, v49, v145, v185
	v_cvt_pk_bf16_f32 v46, v46, v47
	v_cvt_pk_bf16_f32 v47, v48, v49
	s_waitcnt vmcnt(2)
	v_fma_f32 v42, v42, v146, v186
	v_fma_f32 v43, v43, v147, v187
	v_fma_f32 v44, v44, v148, v188
	v_fma_f32 v45, v45, v149, v189
	v_cvt_pk_bf16_f32 v42, v42, v43
	v_cvt_pk_bf16_f32 v43, v44, v45
	s_waitcnt vmcnt(1)
	v_fma_f32 v38, v38, v142, v190
	v_fma_f32 v39, v39, v143, v191
	v_fma_f32 v40, v40, v144, v192
	v_fma_f32 v41, v41, v145, v193
	v_cvt_pk_bf16_f32 v38, v38, v39
	v_cvt_pk_bf16_f32 v39, v40, v41
	s_waitcnt vmcnt(0)
	v_fma_f32 v34, v34, v146, v194
	v_fma_f32 v35, v35, v147, v195
	v_fma_f32 v36, v36, v148, v196
	v_fma_f32 v37, v37, v149, v197
	v_cvt_pk_bf16_f32 v34, v34, v35
	v_cvt_pk_bf16_f32 v35, v36, v37
	global_load_dwordx4 v[166:169], v138, s[12:13]
	global_load_dwordx4 v[170:173], v138, s[12:13] offset:64
	s_add_u32 s12, s12, 0x20000
	s_addc_u32 s13, s13, 0
	global_load_dwordx4 v[174:177], v138, s[12:13]
	global_load_dwordx4 v[178:181], v138, s[12:13] offset:64
	s_add_u32 s12, s12, 0x20000
	s_addc_u32 s13, s13, 0
	global_load_dwordx4 v[182:185], v138, s[12:13]
	global_load_dwordx4 v[186:189], v138, s[12:13] offset:64
	s_add_u32 s12, s12, 0x20000
	s_addc_u32 s13, s13, 0
	global_load_dwordx4 v[190:193], v138, s[12:13]
	global_load_dwordx4 v[194:197], v138, s[12:13] offset:64
	s_waitcnt vmcnt(7)
	v_fma_f32 v30, v30, v142, v166
	v_fma_f32 v31, v31, v143, v167
	v_fma_f32 v32, v32, v144, v168
	v_fma_f32 v33, v33, v145, v169
	v_cvt_pk_bf16_f32 v30, v30, v31
	v_cvt_pk_bf16_f32 v31, v32, v33
	s_waitcnt vmcnt(6)
	v_fma_f32 v26, v26, v146, v170
	v_fma_f32 v27, v27, v147, v171
	v_fma_f32 v28, v28, v148, v172
	v_fma_f32 v29, v29, v149, v173
	v_cvt_pk_bf16_f32 v26, v26, v27
	v_cvt_pk_bf16_f32 v27, v28, v29
	s_waitcnt vmcnt(5)
	v_fma_f32 v22, v22, v142, v174
	v_fma_f32 v23, v23, v143, v175
	v_fma_f32 v24, v24, v144, v176
	v_fma_f32 v25, v25, v145, v177
	v_cvt_pk_bf16_f32 v22, v22, v23
	v_cvt_pk_bf16_f32 v23, v24, v25
	s_waitcnt vmcnt(4)
	v_fma_f32 v18, v18, v146, v178
	v_fma_f32 v19, v19, v147, v179
	v_fma_f32 v20, v20, v148, v180
	v_fma_f32 v21, v21, v149, v181
	v_cvt_pk_bf16_f32 v18, v18, v19
	v_cvt_pk_bf16_f32 v19, v20, v21
	s_waitcnt vmcnt(3)
	v_fma_f32 v14, v14, v142, v182
	v_fma_f32 v15, v15, v143, v183
	v_fma_f32 v16, v16, v144, v184
	v_fma_f32 v17, v17, v145, v185
	v_cvt_pk_bf16_f32 v14, v14, v15
	v_cvt_pk_bf16_f32 v15, v16, v17
	s_waitcnt vmcnt(2)
	v_fma_f32 v10, v10, v146, v186
	v_fma_f32 v11, v11, v147, v187
	v_fma_f32 v12, v12, v148, v188
	v_fma_f32 v13, v13, v149, v189
	v_cvt_pk_bf16_f32 v10, v10, v11
	v_cvt_pk_bf16_f32 v11, v12, v13
	s_waitcnt vmcnt(1)
	v_fma_f32 v6, v6, v142, v190
	v_fma_f32 v7, v7, v143, v191
	v_fma_f32 v8, v8, v144, v192
	v_fma_f32 v9, v9, v145, v193
	v_cvt_pk_bf16_f32 v6, v6, v7
	v_cvt_pk_bf16_f32 v7, v8, v9
	s_waitcnt vmcnt(0)
	v_fma_f32 v2, v2, v146, v194
	v_fma_f32 v3, v3, v147, v195
	v_fma_f32 v4, v4, v148, v196
	v_fma_f32 v5, v5, v149, v197
	v_cvt_pk_bf16_f32 v2, v2, v3
	v_cvt_pk_bf16_f32 v3, v4, v5
	v_lshrrev_b32_e32 v138, 1, v133
	v_lshl_add_u32 v138, v134, 2, v138
	v_and_b32_e32 v139, 1, v133
	v_lshlrev_b32_e32 v139, 3, v139
	v_lshl_add_u32 v140, v135, 6, v132
	v_lshlrev_b32_e32 v140, 8, v140
	v_add_u32_e32 v140, v140, v139
	v_mov_b32_e32 v141, v138
	v_xor_b32_e32 v141, v141, v132
	v_lshl_add_u32 v158, v141, 4, v140
	v_add_u32_e32 v141, 2, v138
	v_xor_b32_e32 v141, v141, v132
	v_lshl_add_u32 v159, v141, 4, v140
.Lres_oh_store:
	s_waitcnt lgkmcnt(0)
	s_barrier
	ds_write_b64 v158, v[62:63]
	ds_write_b64 v159, v[58:59]
	ds_write_b64 v158, v[54:55] offset:4096
	ds_write_b64 v159, v[50:51] offset:4096
	ds_write_b64 v158, v[46:47] offset:8192
	ds_write_b64 v159, v[42:43] offset:8192
	ds_write_b64 v158, v[38:39] offset:12288
	ds_write_b64 v159, v[34:35] offset:12288
	ds_write_b64 v158, v[30:31] offset:32768
	ds_write_b64 v159, v[26:27] offset:32768
	ds_write_b64 v158, v[22:23] offset:36864
	ds_write_b64 v159, v[18:19] offset:36864
	ds_write_b64 v158, v[14:15] offset:40960
	ds_write_b64 v159, v[10:11] offset:40960
	ds_write_b64 v158, v[6:7] offset:45056
	ds_write_b64 v159, v[2:3] offset:45056
	v_lshlrev_b32_e32 v198, 4, v130
	v_lshl_add_u32 v198, v131, 10, v198
	v_add_u32_e32 v199, 0x10000, v198
	v_lshrrev_b32_e32 v138, 4, v130
	v_lshl_add_u32 v139, v131, 2, v138
	v_and_b32_e32 v140, 15, v130
	v_and_b32_e32 v141, 15, v139
	v_xor_b32_e32 v140, v140, v141
	v_lshlrev_b32_e32 v200, 12, v139
	v_lshl_add_u32 v200, v140, 4, v200
	s_waitcnt lgkmcnt(0)
	s_barrier
	ds_read_b128 v[166:169], v198
	ds_read_b128 v[170:173], v198 offset:8192
	ds_read_b128 v[174:177], v198 offset:16384
	ds_read_b128 v[178:181], v198 offset:24576
	ds_read_b128 v[182:185], v198 offset:32768
	ds_read_b128 v[186:189], v198 offset:40960
	ds_read_b128 v[190:193], v198 offset:49152
	ds_read_b128 v[194:197], v198 offset:57344
	s_waitcnt lgkmcnt(7)
	global_store_dwordx4 v200, v[166:169], s[16:17]
	s_add_u32 s16, s16, 0x20000
	s_addc_u32 s17, s17, 0
	s_waitcnt lgkmcnt(6)
	global_store_dwordx4 v200, v[170:173], s[16:17]
	s_add_u32 s16, s16, 0x20000
	s_addc_u32 s17, s17, 0
	s_waitcnt lgkmcnt(5)
	global_store_dwordx4 v200, v[174:177], s[16:17]
	s_add_u32 s16, s16, 0x20000
	s_addc_u32 s17, s17, 0
	s_waitcnt lgkmcnt(4)
	global_store_dwordx4 v200, v[178:181], s[16:17]
	s_add_u32 s16, s16, 0x20000
	s_addc_u32 s17, s17, 0
	s_waitcnt lgkmcnt(3)
	global_store_dwordx4 v200, v[182:185], s[16:17]
	s_add_u32 s16, s16, 0x20000
	s_addc_u32 s17, s17, 0
	s_waitcnt lgkmcnt(2)
	global_store_dwordx4 v200, v[186:189], s[16:17]
	s_add_u32 s16, s16, 0x20000
	s_addc_u32 s17, s17, 0
	s_waitcnt lgkmcnt(1)
	global_store_dwordx4 v200, v[190:193], s[16:17]
	s_add_u32 s16, s16, 0x20000
	s_addc_u32 s17, s17, 0
	s_waitcnt lgkmcnt(0)
	global_store_dwordx4 v200, v[194:197], s[16:17]
	v_readlane_b32 s0, v254, 51
	s_add_i32 s53, s53, s0
	v_readlane_b32 s0, v254, 38
	s_add_i32 s52, s52, s0
	s_cmpk_lt_i32 s53, 0x100
	s_cbranch_scc0 .LBB0_175
	s_branch .LBB0_105
.LBB0_175:
	v_readlane_b32 s56, v252, 0
	s_mov_b32 s54, s2
	s_branch .LBB0_177
.LBB0_177:
	v_mov_b32_e32 v142, v206
	s_barrier
	s_ashr_i32 s0, s56, 31
	v_ashrrev_i32_e32 v0, 31, v142
	v_lshrrev_b32_e32 v0, 26, v0
	s_lshr_b32 s0, s0, 29
	v_add_u32_e32 v0, v142, v0
	s_add_i32 s0, s56, s0
	v_ashrrev_i32_e32 v4, 6, v0
	v_bfe_i32 v0, v142, 27, 1
	s_ashr_i32 s1, s0, 3
	s_and_b32 s0, s0, -8
	v_lshlrev_b32_e32 v147, 4, v142
	v_lshrrev_b32_e32 v0, 22, v0
	s_sub_i32 s0, s56, s0
	v_add_u32_e32 v0, v147, v0
	s_lshr_b32 s8, s0, 31
	v_and_b32_e32 v0, 0xfffffc00, v0
	s_or_b32 s8, s8, 48
	v_sub_u32_e32 v0, v147, v0
	s_mul_i32 s0, s8, s0
	v_lshrrev_b32_e32 v2, 4, v0
	s_add_i32 s0, s0, s1
	v_bitop3_b32 v2, v2, v0, 32 bitop3:0x6c
	v_ashrrev_i32_e32 v0, 31, v0
	s_mul_hi_i32 s1, s0, 0x2aaaaaab
	v_lshrrev_b32_e32 v0, 26, v0
	s_lshr_b32 s8, s1, 31
	s_ashr_i32 s1, s1, 5
	v_lshlrev_b32_e32 v3, 3, v4
	v_add_u32_e32 v0, v2, v0
	s_add_i32 s1, s1, s8
	v_and_b32_e32 v3, 0xffff0, v3
	v_ashrrev_i32_e32 v5, 6, v0
	s_mul_i32 s8, s1, 0xc0
	v_add_u32_e32 v0, v5, v3
	v_lshlrev_b32_e32 v3, 5, v4
	s_sub_i32 s0, s0, s8
	v_and_b32_e32 v6, 32, v3
	v_mul_i32_i24_e32 v3, 64, v5
	s_sext_i32_i16 s8, s0
	v_sub_u32_e32 v2, v2, v3
	s_bfe_u32 s8, s8, 0x2001d
	v_ashrrev_i16_sdwa v2, v207, sext(v2) dst_sel:DWORD dst_unused:UNUSED_PAD src0_sel:DWORD src1_sel:BYTE_0
	v_add_u32_e32 v148, 0x2000, v147
	s_add_i32 s8, s0, s8
	v_bfe_i32 v8, v2, 0, 16
	v_ashrrev_i32_e32 v2, 31, v148
	s_sext_i32_i16 s9, s8
	s_and_b32 s8, s8, 0xfffc
	v_lshrrev_b32_e32 v2, 22, v2
	s_sub_i32 s0, s0, s8
	v_add_u32_e32 v2, v148, v2
	s_sext_i32_i16 s0, s0
	v_ashrrev_i32_e32 v7, 10, v2
	s_lshl_b32 s8, s9, 6
	s_lshl_b32 s1, s1, 10
	s_lshl_b32 s0, s0, 8
	v_mul_i32_i24_e32 v2, 0x400, v7
	s_and_b32 s10, s8, 0xffffff00
	s_add_i32 s8, s0, s1
	v_sub_u32_e32 v2, v148, v2
	v_lshrrev_b32_e32 v3, 4, v2
	s_ashr_i32 s9, s8, 31
	v_bitop3_b32 v2, v3, v2, 32 bitop3:0x6c
	s_lshl_b64 s[12:13], s[8:9], 12
	v_ashrrev_i32_e32 v9, 31, v2
	s_add_u32 s0, s57, s12
	v_lshrrev_b32_e32 v9, 26, v9
	s_addc_u32 s1, s63, s13
	s_ashr_i32 s11, s10, 31
	v_readlane_b32 s36, v253, 33
	v_add_u32_e32 v11, v2, v9
	s_lshl_b64 s[14:15], s[10:11], 12
	v_readlane_b32 s48, v253, 45
	v_lshlrev_b32_e32 v3, 3, v7
	v_ashrrev_i32_e32 v9, 6, v11
	v_and_b32_e32 v11, 0xc0, v11
	v_readlane_b32 s49, v253, 46
	s_add_u32 s16, s48, s14
	v_and_b32_e32 v3, 0xffff0, v3
	v_lshlrev_b32_e32 v10, 5, v7
	v_sub_u32_e32 v2, v2, v11
	v_add_u32_e32 v149, 0x10000, v147
	s_addc_u32 s17, s49, s15
	s_or_b32 s52, s8, 0x80
	v_lshl_or_b32 v0, v0, 11, v6
	v_add_u32_e32 v3, v9, v3
	v_and_b32_e32 v10, 32, v10
	v_ashrrev_i16_sdwa v2, v207, sext(v2) dst_sel:DWORD dst_unused:UNUSED_PAD src0_sel:DWORD src1_sel:BYTE_0
	v_readfirstlane_b32 s9, v149
	v_add_u32_e32 v150, 0x12000, v147
	s_ashr_i32 s53, s52, 31
	v_add_lshl_u32 v0, v0, v8, 1
	v_bfe_i32 v11, v2, 0, 16
	v_lshl_or_b32 v2, v3, 11, v10
	s_mov_b32 m0, s9
	v_readfirstlane_b32 s9, v150
	s_lshl_b64 s[52:53], s[52:53], 12
	v_add_lshl_u32 v2, v2, v11, 1
	global_load_lds_dwordx4 v0, s[0:1]
	s_mov_b32 m0, s9
	v_readfirstlane_b32 s9, v147
	s_add_u32 s72, s57, s52
	global_load_lds_dwordx4 v2, s[0:1]
	s_mov_b32 m0, s9
	v_readfirstlane_b32 s9, v148
	s_addc_u32 s73, s63, s53
	v_add_u32_e32 v152, 0x14000, v147
	s_or_b32 s52, s10, 0x80
	global_load_lds_dwordx4 v0, s[16:17]
	s_mov_b32 m0, s9
	v_readfirstlane_b32 s9, v152
	v_add_u32_e32 v153, 0x16000, v147
	s_ashr_i32 s53, s52, 31
	global_load_lds_dwordx4 v2, s[16:17]
	s_mov_b32 m0, s9
	v_readfirstlane_b32 s9, v153
	s_lshl_b64 s[52:53], s[52:53], 12
	v_add_u32_e32 v154, 0x4000, v147
	global_load_lds_dwordx4 v0, s[72:73]
	s_mov_b32 m0, s9
	s_add_u32 s76, s48, s52
	v_readfirstlane_b32 s9, v154
	v_add_u32_e32 v155, 0x6000, v147
	global_load_lds_dwordx4 v2, s[72:73]
	s_addc_u32 s77, s49, s53
	s_mov_b32 m0, s9
	v_readfirstlane_b32 s9, v155
	global_load_lds_dwordx4 v0, s[76:77]
	s_mov_b32 m0, s9
	v_ashrrev_i32_e32 v143, 8, v142
	global_load_lds_dwordx4 v2, s[76:77]
	v_cmp_eq_u32_e32 vcc, 1, v143
	v_readlane_b32 s37, v253, 34
	v_readlane_b32 s38, v253, 35
	v_readlane_b32 s39, v253, 36
	v_readlane_b32 s40, v253, 37
	v_readlane_b32 s41, v253, 38
	v_readlane_b32 s42, v253, 39
	v_readlane_b32 s43, v253, 40
	v_readlane_b32 s44, v253, 41
	v_readlane_b32 s45, v253, 42
	v_readlane_b32 s46, v253, 43
	v_readlane_b32 s47, v253, 44
	v_readlane_b32 s50, v253, 47
	v_readlane_b32 s51, v253, 48
	s_and_saveexec_b64 s[52:53], vcc
	s_cbranch_execz .LBB0_179
	s_barrier

.LBB0_183:
	s_or_b64 exec, exec, s[0:1]
	v_and_b32_e32 v130, 63, v206
	v_lshrrev_b32_e32 v131, 6, v206
	v_and_b32_e32 v132, 15, v206
	v_bfe_u32 v133, v206, 4, 2
	v_and_b32_e32 v134, 3, v131
	v_lshrrev_b32_e32 v135, 2, v131
	v_readfirstlane_b32 s0, v131
	s_sub_u32 s1, s10, 0x1000
	s_lshr_b32 s9, s1, 11
	s_add_u32 s9, s9, 1
	s_cmp_lt_u32 s10, 0x1000
	s_cselect_b32 s9, 0, s9
	s_cselect_b32 s1, s10, s1
	s_cselect_b32 s12, s66, s62
	s_cselect_b32 s13, s96, s64
	s_mul_i32 s9, s9, s65
	s_lshl_b32 s11, s8, 2
	s_add_u32 s14, s6, s9
	s_addc_u32 s15, s7, 0
	s_add_u32 s14, s14, s11
	s_addc_u32 s15, s15, 0
	s_lshl_b32 s9, s10, 12
	s_lshl_b32 s11, s8, 1
	s_add_u32 s16, s22, s9
	s_addc_u32 s17, s23, 0
	s_add_u32 s16, s16, s11
	s_addc_u32 s17, s17, 0
	v_lshlrev_b32_e32 v136, 5, v134
	v_lshl_add_u32 v136, v133, 2, v136
	v_lshlrev_b32_e32 v137, 2, v136
	global_load_dwordx4 v[142:145], v137, s[14:15]
	global_load_dwordx4 v[146:149], v137, s[14:15] offset:64
	global_load_dwordx4 v[150:153], v137, s[14:15] offset:512
	global_load_dwordx4 v[154:157], v137, s[14:15] offset:576
	s_cmp_lg_u64 s[70:71], 0
	s_cbranch_scc0 .Lres_of_f32
	s_lshl_b32 s9, s1, 12
	s_add_u32 s12, s12, s9
	s_addc_u32 s13, s13, 0
	s_add_u32 s12, s12, s11
	s_addc_u32 s13, s13, 0
	v_lshrrev_b32_e32 v138, 5, v130
	v_lshl_add_u32 v139, v131, 1, v138
	v_and_b32_e32 v140, 31, v130
	v_and_b32_e32 v141, 15, v139
	v_xor_b32_e32 v140, v140, v141
	v_lshlrev_b32_e32 v141, 12, v139
	v_lshl_add_u32 v141, v140, 4, v141
	s_lshl_b32 s9, s0, 10
	s_mov_b32 m0, s9
	s_add_i32 s9, s9, 0x2000
	global_load_lds_dwordx4 v141, s[12:13]
	s_add_u32 s12, s12, 0x10000
	s_addc_u32 s13, s13, 0
	s_mov_b32 m0, s9
	s_add_i32 s9, s9, 0x2000
	global_load_lds_dwordx4 v141, s[12:13]
	s_add_u32 s12, s12, 0x10000
	s_addc_u32 s13, s13, 0
	s_mov_b32 m0, s9
	s_add_i32 s9, s9, 0x2000
	global_load_lds_dwordx4 v141, s[12:13]
	s_add_u32 s12, s12, 0x10000
	s_addc_u32 s13, s13, 0
	s_mov_b32 m0, s9
	s_add_i32 s9, s9, 0x2000
	global_load_lds_dwordx4 v141, s[12:13]
	s_add_u32 s12, s12, 0x10000
	s_addc_u32 s13, s13, 0
	s_mov_b32 m0, s9
	s_add_i32 s9, s9, 0x2000
	global_load_lds_dwordx4 v141, s[12:13]
	s_add_u32 s12, s12, 0x10000
	s_addc_u32 s13, s13, 0
	s_mov_b32 m0, s9
	s_add_i32 s9, s9, 0x2000
	global_load_lds_dwordx4 v141, s[12:13]
	s_add_u32 s12, s12, 0x10000
	s_addc_u32 s13, s13, 0
	s_mov_b32 m0, s9
	s_add_i32 s9, s9, 0x2000
	global_load_lds_dwordx4 v141, s[12:13]
	s_add_u32 s12, s12, 0x10000
	s_addc_u32 s13, s13, 0
	s_mov_b32 m0, s9
	s_add_i32 s9, s9, 0x2000
	global_load_lds_dwordx4 v141, s[12:13]
	s_add_u32 s12, s12, 0x10000
	s_addc_u32 s13, s13, 0
	s_mov_b32 m0, s9
	s_add_i32 s9, s9, 0x2000
	global_load_lds_dwordx4 v141, s[12:13]
	s_add_u32 s12, s12, 0x10000
	s_addc_u32 s13, s13, 0
	s_mov_b32 m0, s9
	s_add_i32 s9, s9, 0x2000
	global_load_lds_dwordx4 v141, s[12:13]
	s_add_u32 s12, s12, 0x10000
	s_addc_u32 s13, s13, 0
	s_mov_b32 m0, s9
	s_add_i32 s9, s9, 0x2000
	global_load_lds_dwordx4 v141, s[12:13]
	s_add_u32 s12, s12, 0x10000
	s_addc_u32 s13, s13, 0
	s_mov_b32 m0, s9
	s_add_i32 s9, s9, 0x2000
	global_load_lds_dwordx4 v141, s[12:13]
	s_add_u32 s12, s12, 0x10000
	s_addc_u32 s13, s13, 0
	s_mov_b32 m0, s9
	s_add_i32 s9, s9, 0x2000
	global_load_lds_dwordx4 v141, s[12:13]
	s_add_u32 s12, s12, 0x10000
	s_addc_u32 s13, s13, 0
	s_mov_b32 m0, s9
	s_add_i32 s9, s9, 0x2000
	global_load_lds_dwordx4 v141, s[12:13]
	s_add_u32 s12, s12, 0x10000
	s_addc_u32 s13, s13, 0
	s_mov_b32 m0, s9
	s_add_i32 s9, s9, 0x2000
	global_load_lds_dwordx4 v141, s[12:13]
	s_add_u32 s12, s12, 0x10000
	s_addc_u32 s13, s13, 0
	s_mov_b32 m0, s9
	s_add_i32 s9, s9, 0x2000
	global_load_lds_dwordx4 v141, s[12:13]
	v_lshrrev_b32_e32 v138, 1, v133
	v_lshl_add_u32 v138, v134, 2, v138
	v_and_b32_e32 v139, 1, v133
	v_lshlrev_b32_e32 v139, 3, v139
	v_lshl_add_u32 v140, v135, 6, v132
	v_lshlrev_b32_e32 v140, 9, v140
	v_add_u32_e32 v140, v140, v139
	v_mov_b32_e32 v141, v138
	v_xor_b32_e32 v141, v141, v132
	v_lshl_add_u32 v158, v141, 4, v140
	v_add_u32_e32 v160, 0x10000, v158
	v_add_u32_e32 v141, 2, v138
	v_xor_b32_e32 v141, v141, v132
	v_lshl_add_u32 v159, v141, 4, v140
	v_add_u32_e32 v161, 0x10000, v159
	s_waitcnt vmcnt(0)
	s_barrier
	ds_read_b64 v[162:163], v158
	ds_read_b64 v[164:165], v159
	s_waitcnt lgkmcnt(1)
	v_lshlrev_b32_e32 v166, 16, v162
	v_and_b32_e32 v167, 0xffff0000, v162
	v_lshlrev_b32_e32 v168, 16, v163
	v_and_b32_e32 v169, 0xffff0000, v163
	v_fma_f32 v126, v126, v142, v166
	v_fma_f32 v127, v127, v143, v167
	v_fma_f32 v128, v128, v144, v168
	v_fma_f32 v129, v129, v145, v169
	v_cvt_pk_bf16_f32 v126, v126, v127
	v_cvt_pk_bf16_f32 v127, v128, v129
	ds_read_b64 v[162:163], v158 offset:256
	s_waitcnt lgkmcnt(1)
	v_lshlrev_b32_e32 v166, 16, v164
	v_and_b32_e32 v167, 0xffff0000, v164
	v_lshlrev_b32_e32 v168, 16, v165
	v_and_b32_e32 v169, 0xffff0000, v165
	v_fma_f32 v118, v118, v146, v166
	v_fma_f32 v119, v119, v147, v167
	v_fma_f32 v120, v120, v148, v168
	v_fma_f32 v121, v121, v149, v169
	v_cvt_pk_bf16_f32 v118, v118, v119
	v_cvt_pk_bf16_f32 v119, v120, v121
	ds_read_b64 v[164:165], v159 offset:256
	s_waitcnt lgkmcnt(1)
	v_lshlrev_b32_e32 v166, 16, v162
	v_and_b32_e32 v167, 0xffff0000, v162
	v_lshlrev_b32_e32 v168, 16, v163
	v_and_b32_e32 v169, 0xffff0000, v163
	v_fma_f32 v122, v122, v150, v166
	v_fma_f32 v123, v123, v151, v167
	v_fma_f32 v124, v124, v152, v168
	v_fma_f32 v125, v125, v153, v169
	v_cvt_pk_bf16_f32 v122, v122, v123
	v_cvt_pk_bf16_f32 v123, v124, v125
	ds_read_b64 v[162:163], v158 offset:8192
	s_waitcnt lgkmcnt(1)
	v_lshlrev_b32_e32 v166, 16, v164
	v_and_b32_e32 v167, 0xffff0000, v164
	v_lshlrev_b32_e32 v168, 16, v165
	v_and_b32_e32 v169, 0xffff0000, v165
	v_fma_f32 v114, v114, v154, v166
	v_fma_f32 v115, v115, v155, v167
	v_fma_f32 v116, v116, v156, v168
	v_fma_f32 v117, v117, v157, v169
	v_cvt_pk_bf16_f32 v114, v114, v115
	v_cvt_pk_bf16_f32 v115, v116, v117
	ds_read_b64 v[164:165], v159 offset:8192
	s_waitcnt lgkmcnt(1)
	v_lshlrev_b32_e32 v166, 16, v162
	v_and_b32_e32 v167, 0xffff0000, v162
	v_lshlrev_b32_e32 v168, 16, v163
	v_and_b32_e32 v169, 0xffff0000, v163
	v_fma_f32 v110, v110, v142, v166
	v_fma_f32 v111, v111, v143, v167
	v_fma_f32 v112, v112, v144, v168
	v_fma_f32 v113, v113, v145, v169
	v_cvt_pk_bf16_f32 v110, v110, v111
	v_cvt_pk_bf16_f32 v111, v112, v113
	ds_read_b64 v[162:163], v158 offset:8448
	s_waitcnt lgkmcnt(1)
	v_lshlrev_b32_e32 v166, 16, v164
	v_and_b32_e32 v167, 0xffff0000, v164
	v_lshlrev_b32_e32 v168, 16, v165
	v_and_b32_e32 v169, 0xffff0000, v165
	v_fma_f32 v102, v102, v146, v166
	v_fma_f32 v103, v103, v147, v167
	v_fma_f32 v104, v104, v148, v168
	v_fma_f32 v105, v105, v149, v169
	v_cvt_pk_bf16_f32 v102, v102, v103
	v_cvt_pk_bf16_f32 v103, v104, v105
	ds_read_b64 v[164:165], v159 offset:8448
	s_waitcnt lgkmcnt(1)
	v_lshlrev_b32_e32 v166, 16, v162
	v_and_b32_e32 v167, 0xffff0000, v162
	v_lshlrev_b32_e32 v168, 16, v163
	v_and_b32_e32 v169, 0xffff0000, v163
	v_fma_f32 v106, v106, v150, v166
	v_fma_f32 v107, v107, v151, v167
	v_fma_f32 v108, v108, v152, v168
	v_fma_f32 v109, v109, v153, v169
	v_cvt_pk_bf16_f32 v106, v106, v107
	v_cvt_pk_bf16_f32 v107, v108, v109
	ds_read_b64 v[162:163], v158 offset:16384
	s_waitcnt lgkmcnt(1)
	v_lshlrev_b32_e32 v166, 16, v164
	v_and_b32_e32 v167, 0xffff0000, v164
	v_lshlrev_b32_e32 v168, 16, v165
	v_and_b32_e32 v169, 0xffff0000, v165
	v_fma_f32 v98, v98, v154, v166
	v_fma_f32 v99, v99, v155, v167
	v_fma_f32 v100, v100, v156, v168
	v_fma_f32 v101, v101, v157, v169
	v_cvt_pk_bf16_f32 v98, v98, v99
	v_cvt_pk_bf16_f32 v99, v100, v101
	ds_read_b64 v[164:165], v159 offset:16384
	s_waitcnt lgkmcnt(1)
	v_lshlrev_b32_e32 v166, 16, v162
	v_and_b32_e32 v167, 0xffff0000, v162
	v_lshlrev_b32_e32 v168, 16, v163
	v_and_b32_e32 v169, 0xffff0000, v163
	v_fma_f32 v94, v94, v142, v166
	v_fma_f32 v95, v95, v143, v167
	v_fma_f32 v96, v96, v144, v168
	v_fma_f32 v97, v97, v145, v169
	v_cvt_pk_bf16_f32 v94, v94, v95
	v_cvt_pk_bf16_f32 v95, v96, v97
	ds_read_b64 v[162:163], v158 offset:16640
	s_waitcnt lgkmcnt(1)
	v_lshlrev_b32_e32 v166, 16, v164
	v_and_b32_e32 v167, 0xffff0000, v164
	v_lshlrev_b32_e32 v168, 16, v165
	v_and_b32_e32 v169, 0xffff0000, v165
	v_fma_f32 v86, v86, v146, v166
	v_fma_f32 v87, v87, v147, v167
	v_fma_f32 v88, v88, v148, v168
	v_fma_f32 v89, v89, v149, v169
	v_cvt_pk_bf16_f32 v86, v86, v87
	v_cvt_pk_bf16_f32 v87, v88, v89
	ds_read_b64 v[164:165], v159 offset:16640
	s_waitcnt lgkmcnt(1)
	v_lshlrev_b32_e32 v166, 16, v162
	v_and_b32_e32 v167, 0xffff0000, v162
	v_lshlrev_b32_e32 v168, 16, v163
	v_and_b32_e32 v169, 0xffff0000, v163
	v_fma_f32 v90, v90, v150, v166
	v_fma_f32 v91, v91, v151, v167
	v_fma_f32 v92, v92, v152, v168
	v_fma_f32 v93, v93, v153, v169
	v_cvt_pk_bf16_f32 v90, v90, v91
	v_cvt_pk_bf16_f32 v91, v92, v93
	ds_read_b64 v[162:163], v158 offset:24576
	s_waitcnt lgkmcnt(1)
	v_lshlrev_b32_e32 v166, 16, v164
	v_and_b32_e32 v167, 0xffff0000, v164
	v_lshlrev_b32_e32 v168, 16, v165
	v_and_b32_e32 v169, 0xffff0000, v165
	v_fma_f32 v82, v82, v154, v166
	v_fma_f32 v83, v83, v155, v167
	v_fma_f32 v84, v84, v156, v168
	v_fma_f32 v85, v85, v157, v169
	v_cvt_pk_bf16_f32 v82, v82, v83
	v_cvt_pk_bf16_f32 v83, v84, v85
	ds_read_b64 v[164:165], v159 offset:24576
	s_waitcnt lgkmcnt(1)
	v_lshlrev_b32_e32 v166, 16, v162
	v_and_b32_e32 v167, 0xffff0000, v162
	v_lshlrev_b32_e32 v168, 16, v163
	v_and_b32_e32 v169, 0xffff0000, v163
	v_fma_f32 v78, v78, v142, v166
	v_fma_f32 v79, v79, v143, v167
	v_fma_f32 v80, v80, v144, v168
	v_fma_f32 v81, v81, v145, v169
	v_cvt_pk_bf16_f32 v78, v78, v79
	v_cvt_pk_bf16_f32 v79, v80, v81
	ds_read_b64 v[162:163], v158 offset:24832
	s_waitcnt lgkmcnt(1)
	v_lshlrev_b32_e32 v166, 16, v164
	v_and_b32_e32 v167, 0xffff0000, v164
	v_lshlrev_b32_e32 v168, 16, v165
	v_and_b32_e32 v169, 0xffff0000, v165
	v_fma_f32 v70, v70, v146, v166
	v_fma_f32 v71, v71, v147, v167
	v_fma_f32 v72, v72, v148, v168
	v_fma_f32 v73, v73, v149, v169
	v_cvt_pk_bf16_f32 v70, v70, v71
	v_cvt_pk_bf16_f32 v71, v72, v73
	ds_read_b64 v[164:165], v159 offset:24832
	s_waitcnt lgkmcnt(1)
	v_lshlrev_b32_e32 v166, 16, v162
	v_and_b32_e32 v167, 0xffff0000, v162
	v_lshlrev_b32_e32 v168, 16, v163
	v_and_b32_e32 v169, 0xffff0000, v163
	v_fma_f32 v74, v74, v150, v166
	v_fma_f32 v75, v75, v151, v167
	v_fma_f32 v76, v76, v152, v168
	v_fma_f32 v77, v77, v153, v169
	v_cvt_pk_bf16_f32 v74, v74, v75
	v_cvt_pk_bf16_f32 v75, v76, v77
	ds_read_b64 v[162:163], v160
	s_waitcnt lgkmcnt(1)
	v_lshlrev_b32_e32 v166, 16, v164
	v_and_b32_e32 v167, 0xffff0000, v164
	v_lshlrev_b32_e32 v168, 16, v165
	v_and_b32_e32 v169, 0xffff0000, v165
	v_fma_f32 v66, v66, v154, v166
	v_fma_f32 v67, v67, v155, v167
	v_fma_f32 v68, v68, v156, v168
	v_fma_f32 v69, v69, v157, v169
	v_cvt_pk_bf16_f32 v66, v66, v67
	v_cvt_pk_bf16_f32 v67, v68, v69
	ds_read_b64 v[164:165], v161
	s_waitcnt lgkmcnt(1)
	v_lshlrev_b32_e32 v166, 16, v162
	v_and_b32_e32 v167, 0xffff0000, v162
	v_lshlrev_b32_e32 v168, 16, v163
	v_and_b32_e32 v169, 0xffff0000, v163
	v_fma_f32 v62, v62, v142, v166
	v_fma_f32 v63, v63, v143, v167
	v_fma_f32 v64, v64, v144, v168
	v_fma_f32 v65, v65, v145, v169
	v_cvt_pk_bf16_f32 v62, v62, v63
	v_cvt_pk_bf16_f32 v63, v64, v65
	ds_read_b64 v[162:163], v160 offset:256
	s_waitcnt lgkmcnt(1)
	v_lshlrev_b32_e32 v166, 16, v164
	v_and_b32_e32 v167, 0xffff0000, v164
	v_lshlrev_b32_e32 v168, 16, v165
	v_and_b32_e32 v169, 0xffff0000, v165
	v_fma_f32 v54, v54, v146, v166
	v_fma_f32 v55, v55, v147, v167
	v_fma_f32 v56, v56, v148, v168
	v_fma_f32 v57, v57, v149, v169
	v_cvt_pk_bf16_f32 v54, v54, v55
	v_cvt_pk_bf16_f32 v55, v56, v57
	ds_read_b64 v[164:165], v161 offset:256
	s_waitcnt lgkmcnt(1)
	v_lshlrev_b32_e32 v166, 16, v162
	v_and_b32_e32 v167, 0xffff0000, v162
	v_lshlrev_b32_e32 v168, 16, v163
	v_and_b32_e32 v169, 0xffff0000, v163
	v_fma_f32 v58, v58, v150, v166
	v_fma_f32 v59, v59, v151, v167
	v_fma_f32 v60, v60, v152, v168
	v_fma_f32 v61, v61, v153, v169
	v_cvt_pk_bf16_f32 v58, v58, v59
	v_cvt_pk_bf16_f32 v59, v60, v61
	ds_read_b64 v[162:163], v160 offset:8192
	s_waitcnt lgkmcnt(1)
	v_lshlrev_b32_e32 v166, 16, v164
	v_and_b32_e32 v167, 0xffff0000, v164
	v_lshlrev_b32_e32 v168, 16, v165
	v_and_b32_e32 v169, 0xffff0000, v165
	v_fma_f32 v50, v50, v154, v166
	v_fma_f32 v51, v51, v155, v167
	v_fma_f32 v52, v52, v156, v168
	v_fma_f32 v53, v53, v157, v169
	v_cvt_pk_bf16_f32 v50, v50, v51
	v_cvt_pk_bf16_f32 v51, v52, v53
	ds_read_b64 v[164:165], v161 offset:8192
	s_waitcnt lgkmcnt(1)
	v_lshlrev_b32_e32 v166, 16, v162
	v_and_b32_e32 v167, 0xffff0000, v162
	v_lshlrev_b32_e32 v168, 16, v163
	v_and_b32_e32 v169, 0xffff0000, v163
	v_fma_f32 v46, v46, v142, v166
	v_fma_f32 v47, v47, v143, v167
	v_fma_f32 v48, v48, v144, v168
	v_fma_f32 v49, v49, v145, v169
	v_cvt_pk_bf16_f32 v46, v46, v47
	v_cvt_pk_bf16_f32 v47, v48, v49
	ds_read_b64 v[162:163], v160 offset:8448
	s_waitcnt lgkmcnt(1)
	v_lshlrev_b32_e32 v166, 16, v164
	v_and_b32_e32 v167, 0xffff0000, v164
	v_lshlrev_b32_e32 v168, 16, v165
	v_and_b32_e32 v169, 0xffff0000, v165
	v_fma_f32 v38, v38, v146, v166
	v_fma_f32 v39, v39, v147, v167
	v_fma_f32 v40, v40, v148, v168
	v_fma_f32 v41, v41, v149, v169
	v_cvt_pk_bf16_f32 v38, v38, v39
	v_cvt_pk_bf16_f32 v39, v40, v41
	ds_read_b64 v[164:165], v161 offset:8448
	s_waitcnt lgkmcnt(1)
	v_lshlrev_b32_e32 v166, 16, v162
	v_and_b32_e32 v167, 0xffff0000, v162
	v_lshlrev_b32_e32 v168, 16, v163
	v_and_b32_e32 v169, 0xffff0000, v163
	v_fma_f32 v42, v42, v150, v166
	v_fma_f32 v43, v43, v151, v167
	v_fma_f32 v44, v44, v152, v168
	v_fma_f32 v45, v45, v153, v169
	v_cvt_pk_bf16_f32 v42, v42, v43
	v_cvt_pk_bf16_f32 v43, v44, v45
	ds_read_b64 v[162:163], v160 offset:16384
	s_waitcnt lgkmcnt(1)
	v_lshlrev_b32_e32 v166, 16, v164
	v_and_b32_e32 v167, 0xffff0000, v164
	v_lshlrev_b32_e32 v168, 16, v165
	v_and_b32_e32 v169, 0xffff0000, v165
	v_fma_f32 v34, v34, v154, v166
	v_fma_f32 v35, v35, v155, v167
	v_fma_f32 v36, v36, v156, v168
	v_fma_f32 v37, v37, v157, v169
	v_cvt_pk_bf16_f32 v34, v34, v35
	v_cvt_pk_bf16_f32 v35, v36, v37
	ds_read_b64 v[164:165], v161 offset:16384
	s_waitcnt lgkmcnt(1)
	v_lshlrev_b32_e32 v166, 16, v162
	v_and_b32_e32 v167, 0xffff0000, v162
	v_lshlrev_b32_e32 v168, 16, v163
	v_and_b32_e32 v169, 0xffff0000, v163
	v_fma_f32 v30, v30, v142, v166
	v_fma_f32 v31, v31, v143, v167
	v_fma_f32 v32, v32, v144, v168
	v_fma_f32 v33, v33, v145, v169
	v_cvt_pk_bf16_f32 v30, v30, v31
	v_cvt_pk_bf16_f32 v31, v32, v33
	ds_read_b64 v[162:163], v160 offset:16640
	s_waitcnt lgkmcnt(1)
	v_lshlrev_b32_e32 v166, 16, v164
	v_and_b32_e32 v167, 0xffff0000, v164
	v_lshlrev_b32_e32 v168, 16, v165
	v_and_b32_e32 v169, 0xffff0000, v165
	v_fma_f32 v22, v22, v146, v166
	v_fma_f32 v23, v23, v147, v167
	v_fma_f32 v24, v24, v148, v168
	v_fma_f32 v25, v25, v149, v169
	v_cvt_pk_bf16_f32 v22, v22, v23
	v_cvt_pk_bf16_f32 v23, v24, v25
	ds_read_b64 v[164:165], v161 offset:16640
	s_waitcnt lgkmcnt(1)
	v_lshlrev_b32_e32 v166, 16, v162
	v_and_b32_e32 v167, 0xffff0000, v162
	v_lshlrev_b32_e32 v168, 16, v163
	v_and_b32_e32 v169, 0xffff0000, v163
	v_fma_f32 v26, v26, v150, v166
	v_fma_f32 v27, v27, v151, v167
	v_fma_f32 v28, v28, v152, v168
	v_fma_f32 v29, v29, v153, v169
	v_cvt_pk_bf16_f32 v26, v26, v27
	v_cvt_pk_bf16_f32 v27, v28, v29
	ds_read_b64 v[162:163], v160 offset:24576
	s_waitcnt lgkmcnt(1)
	v_lshlrev_b32_e32 v166, 16, v164
	v_and_b32_e32 v167, 0xffff0000, v164
	v_lshlrev_b32_e32 v168, 16, v165
	v_and_b32_e32 v169, 0xffff0000, v165
	v_fma_f32 v18, v18, v154, v166
	v_fma_f32 v19, v19, v155, v167
	v_fma_f32 v20, v20, v156, v168
	v_fma_f32 v21, v21, v157, v169
	v_cvt_pk_bf16_f32 v18, v18, v19
	v_cvt_pk_bf16_f32 v19, v20, v21
	ds_read_b64 v[164:165], v161 offset:24576
	s_waitcnt lgkmcnt(1)
	v_lshlrev_b32_e32 v166, 16, v162
	v_and_b32_e32 v167, 0xffff0000, v162
	v_lshlrev_b32_e32 v168, 16, v163
	v_and_b32_e32 v169, 0xffff0000, v163
	v_fma_f32 v14, v14, v142, v166
	v_fma_f32 v15, v15, v143, v167
	v_fma_f32 v16, v16, v144, v168
	v_fma_f32 v17, v17, v145, v169
	v_cvt_pk_bf16_f32 v14, v14, v15
	v_cvt_pk_bf16_f32 v15, v16, v17
	ds_read_b64 v[162:163], v160 offset:24832
	s_waitcnt lgkmcnt(1)
	v_lshlrev_b32_e32 v166, 16, v164
	v_and_b32_e32 v167, 0xffff0000, v164
	v_lshlrev_b32_e32 v168, 16, v165
	v_and_b32_e32 v169, 0xffff0000, v165
	v_fma_f32 v6, v6, v146, v166
	v_fma_f32 v7, v7, v147, v167
	v_fma_f32 v8, v8, v148, v168
	v_fma_f32 v9, v9, v149, v169
	v_cvt_pk_bf16_f32 v6, v6, v7
	v_cvt_pk_bf16_f32 v7, v8, v9
	ds_read_b64 v[164:165], v161 offset:24832
	s_waitcnt lgkmcnt(1)
	v_lshlrev_b32_e32 v166, 16, v162
	v_and_b32_e32 v167, 0xffff0000, v162
	v_lshlrev_b32_e32 v168, 16, v163
	v_and_b32_e32 v169, 0xffff0000, v163
	v_fma_f32 v10, v10, v150, v166
	v_fma_f32 v11, v11, v151, v167
	v_fma_f32 v12, v12, v152, v168
	v_fma_f32 v13, v13, v153, v169
	v_cvt_pk_bf16_f32 v10, v10, v11
	v_cvt_pk_bf16_f32 v11, v12, v13
	s_waitcnt lgkmcnt(0)
	v_lshlrev_b32_e32 v166, 16, v164
	v_and_b32_e32 v167, 0xffff0000, v164
	v_lshlrev_b32_e32 v168, 16, v165
	v_and_b32_e32 v169, 0xffff0000, v165
	v_fma_f32 v2, v2, v154, v166
	v_fma_f32 v3, v3, v155, v167
	v_fma_f32 v4, v4, v156, v168
	v_fma_f32 v5, v5, v157, v169
	v_cvt_pk_bf16_f32 v2, v2, v3
	v_cvt_pk_bf16_f32 v3, v4, v5
	s_branch .Lres_of_store
.Lres_of_f32:
	s_lshl_b32 s9, s1, 13
	s_add_u32 s12, s12, s9
	s_addc_u32 s13, s13, 0
	s_lshl_b32 s11, s8, 2
	s_add_u32 s12, s12, s11
	s_addc_u32 s13, s13, 0
	v_lshl_add_u32 v138, v135, 6, v132
	v_lshlrev_b32_e32 v138, 13, v138
	v_add_u32_e32 v138, v138, v137
	global_load_dwordx4 v[166:169], v138, s[12:13]
	global_load_dwordx4 v[170:173], v138, s[12:13] offset:64
	global_load_dwordx4 v[174:177], v138, s[12:13] offset:512
	global_load_dwordx4 v[178:181], v138, s[12:13] offset:576
	s_add_u32 s12, s12, 0x20000
	s_addc_u32 s13, s13, 0
	global_load_dwordx4 v[182:185], v138, s[12:13]
	global_load_dwordx4 v[186:189], v138, s[12:13] offset:64
	global_load_dwordx4 v[190:193], v138, s[12:13] offset:512
	global_load_dwordx4 v[194:197], v138, s[12:13] offset:576
	s_add_u32 s12, s12, 0x20000
	s_addc_u32 s13, s13, 0
	s_waitcnt vmcnt(7)
	v_fma_f32 v126, v126, v142, v166
	v_fma_f32 v127, v127, v143, v167
	v_fma_f32 v128, v128, v144, v168
	v_fma_f32 v129, v129, v145, v169
	v_cvt_pk_bf16_f32 v126, v126, v127
	v_cvt_pk_bf16_f32 v127, v128, v129
	s_waitcnt vmcnt(6)
	v_fma_f32 v118, v118, v146, v170
	v_fma_f32 v119, v119, v147, v171
	v_fma_f32 v120, v120, v148, v172
	v_fma_f32 v121, v121, v149, v173
	v_cvt_pk_bf16_f32 v118, v118, v119
	v_cvt_pk_bf16_f32 v119, v120, v121
	s_waitcnt vmcnt(5)
	v_fma_f32 v122, v122, v150, v174
	v_fma_f32 v123, v123, v151, v175
	v_fma_f32 v124, v124, v152, v176
	v_fma_f32 v125, v125, v153, v177
	v_cvt_pk_bf16_f32 v122, v122, v123
	v_cvt_pk_bf16_f32 v123, v124, v125
	s_waitcnt vmcnt(4)
	v_fma_f32 v114, v114, v154, v178
	v_fma_f32 v115, v115, v155, v179
	v_fma_f32 v116, v116, v156, v180
	v_fma_f32 v117, v117, v157, v181
	v_cvt_pk_bf16_f32 v114, v114, v115
	v_cvt_pk_bf16_f32 v115, v116, v117
	s_waitcnt vmcnt(3)
	v_fma_f32 v110, v110, v142, v182
	v_fma_f32 v111, v111, v143, v183
	v_fma_f32 v112, v112, v144, v184
	v_fma_f32 v113, v113, v145, v185
	v_cvt_pk_bf16_f32 v110, v110, v111
	v_cvt_pk_bf16_f32 v111, v112, v113
	s_waitcnt vmcnt(2)
	v_fma_f32 v102, v102, v146, v186
	v_fma_f32 v103, v103, v147, v187
	v_fma_f32 v104, v104, v148, v188
	v_fma_f32 v105, v105, v149, v189
	v_cvt_pk_bf16_f32 v102, v102, v103
	v_cvt_pk_bf16_f32 v103, v104, v105
	s_waitcnt vmcnt(1)
	v_fma_f32 v106, v106, v150, v190
	v_fma_f32 v107, v107, v151, v191
	v_fma_f32 v108, v108, v152, v192
	v_fma_f32 v109, v109, v153, v193
	v_cvt_pk_bf16_f32 v106, v106, v107
	v_cvt_pk_bf16_f32 v107, v108, v109
	s_waitcnt vmcnt(0)
	v_fma_f32 v98, v98, v154, v194
	v_fma_f32 v99, v99, v155, v195
	v_fma_f32 v100, v100, v156, v196
	v_fma_f32 v101, v101, v157, v197
	v_cvt_pk_bf16_f32 v98, v98, v99
	v_cvt_pk_bf16_f32 v99, v100, v101
	global_load_dwordx4 v[166:169], v138, s[12:13]
	global_load_dwordx4 v[170:173], v138, s[12:13] offset:64
	global_load_dwordx4 v[174:177], v138, s[12:13] offset:512
	global_load_dwordx4 v[178:181], v138, s[12:13] offset:576
	s_add_u32 s12, s12, 0x20000
	s_addc_u32 s13, s13, 0
	global_load_dwordx4 v[182:185], v138, s[12:13]
	global_load_dwordx4 v[186:189], v138, s[12:13] offset:64
	global_load_dwordx4 v[190:193], v138, s[12:13] offset:512
	global_load_dwordx4 v[194:197], v138, s[12:13] offset:576
	s_add_u32 s12, s12, 0xa0000
	s_addc_u32 s13, s13, 0
	s_waitcnt vmcnt(7)
	v_fma_f32 v94, v94, v142, v166
	v_fma_f32 v95, v95, v143, v167
	v_fma_f32 v96, v96, v144, v168
	v_fma_f32 v97, v97, v145, v169
	v_cvt_pk_bf16_f32 v94, v94, v95
	v_cvt_pk_bf16_f32 v95, v96, v97
	s_waitcnt vmcnt(6)
	v_fma_f32 v86, v86, v146, v170
	v_fma_f32 v87, v87, v147, v171
	v_fma_f32 v88, v88, v148, v172
	v_fma_f32 v89, v89, v149, v173
	v_cvt_pk_bf16_f32 v86, v86, v87
	v_cvt_pk_bf16_f32 v87, v88, v89
	s_waitcnt vmcnt(5)
	v_fma_f32 v90, v90, v150, v174
	v_fma_f32 v91, v91, v151, v175
	v_fma_f32 v92, v92, v152, v176
	v_fma_f32 v93, v93, v153, v177
	v_cvt_pk_bf16_f32 v90, v90, v91
	v_cvt_pk_bf16_f32 v91, v92, v93
	s_waitcnt vmcnt(4)
	v_fma_f32 v82, v82, v154, v178
	v_fma_f32 v83, v83, v155, v179
	v_fma_f32 v84, v84, v156, v180
	v_fma_f32 v85, v85, v157, v181
	v_cvt_pk_bf16_f32 v82, v82, v83
	v_cvt_pk_bf16_f32 v83, v84, v85
	s_waitcnt vmcnt(3)
	v_fma_f32 v78, v78, v142, v182
	v_fma_f32 v79, v79, v143, v183
	v_fma_f32 v80, v80, v144, v184
	v_fma_f32 v81, v81, v145, v185
	v_cvt_pk_bf16_f32 v78, v78, v79
	v_cvt_pk_bf16_f32 v79, v80, v81
	s_waitcnt vmcnt(2)
	v_fma_f32 v70, v70, v146, v186
	v_fma_f32 v71, v71, v147, v187
	v_fma_f32 v72, v72, v148, v188
	v_fma_f32 v73, v73, v149, v189
	v_cvt_pk_bf16_f32 v70, v70, v71
	v_cvt_pk_bf16_f32 v71, v72, v73
	s_waitcnt vmcnt(1)
	v_fma_f32 v74, v74, v150, v190
	v_fma_f32 v75, v75, v151, v191
	v_fma_f32 v76, v76, v152, v192
	v_fma_f32 v77, v77, v153, v193
	v_cvt_pk_bf16_f32 v74, v74, v75
	v_cvt_pk_bf16_f32 v75, v76, v77
	s_waitcnt vmcnt(0)
	v_fma_f32 v66, v66, v154, v194
	v_fma_f32 v67, v67, v155, v195
	v_fma_f32 v68, v68, v156, v196
	v_fma_f32 v69, v69, v157, v197
	v_cvt_pk_bf16_f32 v66, v66, v67
	v_cvt_pk_bf16_f32 v67, v68, v69
	global_load_dwordx4 v[166:169], v138, s[12:13]
	global_load_dwordx4 v[170:173], v138, s[12:13] offset:64
	global_load_dwordx4 v[174:177], v138, s[12:13] offset:512
	global_load_dwordx4 v[178:181], v138, s[12:13] offset:576
	s_add_u32 s12, s12, 0x20000
	s_addc_u32 s13, s13, 0
	global_load_dwordx4 v[182:185], v138, s[12:13]
	global_load_dwordx4 v[186:189], v138, s[12:13] offset:64
	global_load_dwordx4 v[190:193], v138, s[12:13] offset:512
	global_load_dwordx4 v[194:197], v138, s[12:13] offset:576
	s_add_u32 s12, s12, 0x20000
	s_addc_u32 s13, s13, 0
	s_waitcnt vmcnt(7)
	v_fma_f32 v62, v62, v142, v166
	v_fma_f32 v63, v63, v143, v167
	v_fma_f32 v64, v64, v144, v168
	v_fma_f32 v65, v65, v145, v169
	v_cvt_pk_bf16_f32 v62, v62, v63
	v_cvt_pk_bf16_f32 v63, v64, v65
	s_waitcnt vmcnt(6)
	v_fma_f32 v54, v54, v146, v170
	v_fma_f32 v55, v55, v147, v171
	v_fma_f32 v56, v56, v148, v172
	v_fma_f32 v57, v57, v149, v173
	v_cvt_pk_bf16_f32 v54, v54, v55
	v_cvt_pk_bf16_f32 v55, v56, v57
	s_waitcnt vmcnt(5)
	v_fma_f32 v58, v58, v150, v174
	v_fma_f32 v59, v59, v151, v175
	v_fma_f32 v60, v60, v152, v176
	v_fma_f32 v61, v61, v153, v177
	v_cvt_pk_bf16_f32 v58, v58, v59
	v_cvt_pk_bf16_f32 v59, v60, v61
	s_waitcnt vmcnt(4)
	v_fma_f32 v50, v50, v154, v178
	v_fma_f32 v51, v51, v155, v179
	v_fma_f32 v52, v52, v156, v180
	v_fma_f32 v53, v53, v157, v181
	v_cvt_pk_bf16_f32 v50, v50, v51
	v_cvt_pk_bf16_f32 v51, v52, v53
	s_waitcnt vmcnt(3)
	v_fma_f32 v46, v46, v142, v182
	v_fma_f32 v47, v47, v143, v183
	v_fma_f32 v48, v48, v144, v184
	v_fma_f32 v49, v49, v145, v185
	v_cvt_pk_bf16_f32 v46, v46, v47
	v_cvt_pk_bf16_f32 v47, v48, v49
	s_waitcnt vmcnt(2)
	v_fma_f32 v38, v38, v146, v186
	v_fma_f32 v39, v39, v147, v187
	v_fma_f32 v40, v40, v148, v188
	v_fma_f32 v41, v41, v149, v189
	v_cvt_pk_bf16_f32 v38, v38, v39
	v_cvt_pk_bf16_f32 v39, v40, v41
	s_waitcnt vmcnt(1)
	v_fma_f32 v42, v42, v150, v190
	v_fma_f32 v43, v43, v151, v191
	v_fma_f32 v44, v44, v152, v192
	v_fma_f32 v45, v45, v153, v193
	v_cvt_pk_bf16_f32 v42, v42, v43
	v_cvt_pk_bf16_f32 v43, v44, v45
	s_waitcnt vmcnt(0)
	v_fma_f32 v34, v34, v154, v194
	v_fma_f32 v35, v35, v155, v195
	v_fma_f32 v36, v36, v156, v196
	v_fma_f32 v37, v37, v157, v197
	v_cvt_pk_bf16_f32 v34, v34, v35
	v_cvt_pk_bf16_f32 v35, v36, v37
	global_load_dwordx4 v[166:169], v138, s[12:13]
	global_load_dwordx4 v[170:173], v138, s[12:13] offset:64
	global_load_dwordx4 v[174:177], v138, s[12:13] offset:512
	global_load_dwordx4 v[178:181], v138, s[12:13] offset:576
	s_add_u32 s12, s12, 0x20000
	s_addc_u32 s13, s13, 0
	global_load_dwordx4 v[182:185], v138, s[12:13]
	global_load_dwordx4 v[186:189], v138, s[12:13] offset:64
	global_load_dwordx4 v[190:193], v138, s[12:13] offset:512
	global_load_dwordx4 v[194:197], v138, s[12:13] offset:576
	s_waitcnt vmcnt(7)
	v_fma_f32 v30, v30, v142, v166
	v_fma_f32 v31, v31, v143, v167
	v_fma_f32 v32, v32, v144, v168
	v_fma_f32 v33, v33, v145, v169
	v_cvt_pk_bf16_f32 v30, v30, v31
	v_cvt_pk_bf16_f32 v31, v32, v33
	s_waitcnt vmcnt(6)
	v_fma_f32 v22, v22, v146, v170
	v_fma_f32 v23, v23, v147, v171
	v_fma_f32 v24, v24, v148, v172
	v_fma_f32 v25, v25, v149, v173
	v_cvt_pk_bf16_f32 v22, v22, v23
	v_cvt_pk_bf16_f32 v23, v24, v25
	s_waitcnt vmcnt(5)
	v_fma_f32 v26, v26, v150, v174
	v_fma_f32 v27, v27, v151, v175
	v_fma_f32 v28, v28, v152, v176
	v_fma_f32 v29, v29, v153, v177
	v_cvt_pk_bf16_f32 v26, v26, v27
	v_cvt_pk_bf16_f32 v27, v28, v29
	s_waitcnt vmcnt(4)
	v_fma_f32 v18, v18, v154, v178
	v_fma_f32 v19, v19, v155, v179
	v_fma_f32 v20, v20, v156, v180
	v_fma_f32 v21, v21, v157, v181
	v_cvt_pk_bf16_f32 v18, v18, v19
	v_cvt_pk_bf16_f32 v19, v20, v21
	s_waitcnt vmcnt(3)
	v_fma_f32 v14, v14, v142, v182
	v_fma_f32 v15, v15, v143, v183
	v_fma_f32 v16, v16, v144, v184
	v_fma_f32 v17, v17, v145, v185
	v_cvt_pk_bf16_f32 v14, v14, v15
	v_cvt_pk_bf16_f32 v15, v16, v17
	s_waitcnt vmcnt(2)
	v_fma_f32 v6, v6, v146, v186
	v_fma_f32 v7, v7, v147, v187
	v_fma_f32 v8, v8, v148, v188
	v_fma_f32 v9, v9, v149, v189
	v_cvt_pk_bf16_f32 v6, v6, v7
	v_cvt_pk_bf16_f32 v7, v8, v9
	s_waitcnt vmcnt(1)
	v_fma_f32 v10, v10, v150, v190
	v_fma_f32 v11, v11, v151, v191
	v_fma_f32 v12, v12, v152, v192
	v_fma_f32 v13, v13, v153, v193
	v_cvt_pk_bf16_f32 v10, v10, v11
	v_cvt_pk_bf16_f32 v11, v12, v13
	s_waitcnt vmcnt(0)
	v_fma_f32 v2, v2, v154, v194
	v_fma_f32 v3, v3, v155, v195
	v_fma_f32 v4, v4, v156, v196
	v_fma_f32 v5, v5, v157, v197
	v_cvt_pk_bf16_f32 v2, v2, v3
	v_cvt_pk_bf16_f32 v3, v4, v5
	v_lshrrev_b32_e32 v138, 1, v133
	v_lshl_add_u32 v138, v134, 2, v138
	v_and_b32_e32 v139, 1, v133
	v_lshlrev_b32_e32 v139, 3, v139
	v_lshl_add_u32 v140, v135, 6, v132
	v_lshlrev_b32_e32 v140, 9, v140
	v_add_u32_e32 v140, v140, v139
	v_mov_b32_e32 v141, v138
	v_xor_b32_e32 v141, v141, v132
	v_lshl_add_u32 v158, v141, 4, v140
	v_add_u32_e32 v160, 0x10000, v158
	v_add_u32_e32 v141, 2, v138
	v_xor_b32_e32 v141, v141, v132
	v_lshl_add_u32 v159, v141, 4, v140
	v_add_u32_e32 v161, 0x10000, v159
.Lres_of_store:
	s_waitcnt lgkmcnt(0)
	s_barrier
	ds_write_b64 v158, v[126:127]
	ds_write_b64 v159, v[118:119]
	ds_write_b64 v158, v[122:123] offset:256
	ds_write_b64 v159, v[114:115] offset:256
	ds_write_b64 v158, v[110:111] offset:8192
	ds_write_b64 v159, v[102:103] offset:8192
	ds_write_b64 v158, v[106:107] offset:8448
	ds_write_b64 v159, v[98:99] offset:8448
	ds_write_b64 v158, v[94:95] offset:16384
	ds_write_b64 v159, v[86:87] offset:16384
	ds_write_b64 v158, v[90:91] offset:16640
	ds_write_b64 v159, v[82:83] offset:16640
	ds_write_b64 v158, v[78:79] offset:24576
	ds_write_b64 v159, v[70:71] offset:24576
	ds_write_b64 v158, v[74:75] offset:24832
	ds_write_b64 v159, v[66:67] offset:24832
	ds_write_b64 v160, v[62:63]
	ds_write_b64 v161, v[54:55]
	ds_write_b64 v160, v[58:59] offset:256
	ds_write_b64 v161, v[50:51] offset:256
	ds_write_b64 v160, v[46:47] offset:8192
	ds_write_b64 v161, v[38:39] offset:8192
	ds_write_b64 v160, v[42:43] offset:8448
	ds_write_b64 v161, v[34:35] offset:8448
	ds_write_b64 v160, v[30:31] offset:16384
	ds_write_b64 v161, v[22:23] offset:16384
	ds_write_b64 v160, v[26:27] offset:16640
	ds_write_b64 v161, v[18:19] offset:16640
	ds_write_b64 v160, v[14:15] offset:24576
	ds_write_b64 v161, v[6:7] offset:24576
	ds_write_b64 v160, v[10:11] offset:24832
	ds_write_b64 v161, v[2:3] offset:24832
	v_lshlrev_b32_e32 v198, 4, v130
	v_lshl_add_u32 v198, v131, 10, v198
	v_add_u32_e32 v199, 0x10000, v198
	v_lshrrev_b32_e32 v138, 5, v130
	v_lshl_add_u32 v139, v131, 1, v138
	v_and_b32_e32 v140, 31, v130
	v_and_b32_e32 v141, 15, v139
	v_xor_b32_e32 v140, v140, v141
	v_lshlrev_b32_e32 v200, 12, v139
	v_lshl_add_u32 v200, v140, 4, v200
	s_waitcnt lgkmcnt(0)
	s_barrier
	ds_read_b128 v[166:169], v198
	ds_read_b128 v[170:173], v198 offset:8192
	ds_read_b128 v[174:177], v198 offset:16384
	ds_read_b128 v[178:181], v198 offset:24576
	ds_read_b128 v[182:185], v198 offset:32768
	ds_read_b128 v[186:189], v198 offset:40960
	ds_read_b128 v[190:193], v198 offset:49152
	ds_read_b128 v[194:197], v198 offset:57344
	s_waitcnt lgkmcnt(7)
	global_store_dwordx4 v200, v[166:169], s[16:17]
	s_add_u32 s16, s16, 0x10000
	s_addc_u32 s17, s17, 0
	s_nop 0
	ds_read_b128 v[166:169], v199
	s_waitcnt lgkmcnt(7)
	global_store_dwordx4 v200, v[170:173], s[16:17]
	s_add_u32 s16, s16, 0x10000
	s_addc_u32 s17, s17, 0
	s_nop 0
	ds_read_b128 v[170:173], v199 offset:8192
	s_waitcnt lgkmcnt(7)
	global_store_dwordx4 v200, v[174:177], s[16:17]
	s_add_u32 s16, s16, 0x10000
	s_addc_u32 s17, s17, 0
	s_nop 0
	ds_read_b128 v[174:177], v199 offset:16384
	s_waitcnt lgkmcnt(7)
	global_store_dwordx4 v200, v[178:181], s[16:17]
	s_add_u32 s16, s16, 0x10000
	s_addc_u32 s17, s17, 0
	s_nop 0
	ds_read_b128 v[178:181], v199 offset:24576
	s_waitcnt lgkmcnt(7)
	global_store_dwordx4 v200, v[182:185], s[16:17]
	s_add_u32 s16, s16, 0x10000
	s_addc_u32 s17, s17, 0
	s_nop 0
	ds_read_b128 v[182:185], v199 offset:32768
	s_waitcnt lgkmcnt(7)
	global_store_dwordx4 v200, v[186:189], s[16:17]
	s_add_u32 s16, s16, 0x10000
	s_addc_u32 s17, s17, 0
	s_nop 0
	ds_read_b128 v[186:189], v199 offset:40960
	s_waitcnt lgkmcnt(7)
	global_store_dwordx4 v200, v[190:193], s[16:17]
	s_add_u32 s16, s16, 0x10000
	s_addc_u32 s17, s17, 0
	s_nop 0
	ds_read_b128 v[190:193], v199 offset:49152
	s_waitcnt lgkmcnt(7)
	global_store_dwordx4 v200, v[194:197], s[16:17]
	s_add_u32 s16, s16, 0x10000
	s_addc_u32 s17, s17, 0
	s_nop 0
	ds_read_b128 v[194:197], v199 offset:57344
	s_waitcnt lgkmcnt(7)
	global_store_dwordx4 v200, v[166:169], s[16:17]
	s_add_u32 s16, s16, 0x10000
	s_addc_u32 s17, s17, 0
	s_waitcnt lgkmcnt(6)
	global_store_dwordx4 v200, v[170:173], s[16:17]
	s_add_u32 s16, s16, 0x10000
	s_addc_u32 s17, s17, 0
	s_waitcnt lgkmcnt(5)
	global_store_dwordx4 v200, v[174:177], s[16:17]
	s_add_u32 s16, s16, 0x10000
	s_addc_u32 s17, s17, 0
	s_waitcnt lgkmcnt(4)
	global_store_dwordx4 v200, v[178:181], s[16:17]
	s_add_u32 s16, s16, 0x10000
	s_addc_u32 s17, s17, 0
	s_waitcnt lgkmcnt(3)
	global_store_dwordx4 v200, v[182:185], s[16:17]
	s_add_u32 s16, s16, 0x10000
	s_addc_u32 s17, s17, 0
	s_waitcnt lgkmcnt(2)
	global_store_dwordx4 v200, v[186:189], s[16:17]
	s_add_u32 s16, s16, 0x10000
	s_addc_u32 s17, s17, 0
	s_waitcnt lgkmcnt(1)
	global_store_dwordx4 v200, v[190:193], s[16:17]
	s_add_u32 s16, s16, 0x10000
	s_addc_u32 s17, s17, 0
	s_waitcnt lgkmcnt(0)
	global_store_dwordx4 v200, v[194:197], s[16:17]
	v_readlane_b32 s0, v254, 51
	s_add_i32 s56, s56, s0
	s_cmpk_gt_i32 s56, 0xff
	s_cbranch_scc1 .LBB0_311
	s_branch .LBB0_177
